# v4 plus hand-scheduled jt loops of the SSD output stage (all LDS fragments up front, decay weights for the whole tile, causal mask only on the diagonal tile)
# speedup vs baseline: 1.0104x; 1.0104x over previous
.LBB0_1038:
	v_or_b32_e32 v208, s15, v158
	v_or_b32_e32 v210, s15, v160
	v_or_b32_e32 v211, s15, v144
	v_mad_u32_u24 v208, v208, s53, v142
	v_lshl_add_u32 v209, v210, 2, s13
	v_mad_u32_u24 v211, v211, s33, v143
	ds_read_b128 v[176:179], v208
	ds_read_b128 v[180:183], v208 offset:32
	ds_read_b128 v[184:187], v208 offset:64
	ds_read_b128 v[188:191], v208 offset:96
	ds_read_b128 v[192:195], v208 offset:128
	ds_read_b128 v[196:199], v208 offset:160
	ds_read_b128 v[200:203], v208 offset:192
	ds_read_b128 v[204:207], v208 offset:224
	ds_read_b128 v[220:223], v209
	ds_read_b128 v[224:227], v209 offset:32
	ds_read_b128 v[228:231], v209 offset:64
	ds_read_b128 v[232:235], v209 offset:96
	s_waitcnt lgkmcnt(11)
	v_mfma_f32_32x32x16_bf16 v[20:35], v[176:179], v[68:71], 0
	s_waitcnt lgkmcnt(10)
	v_mfma_f32_32x32x16_bf16 v[20:35], v[180:183], v[72:75], v[20:35]
	s_waitcnt lgkmcnt(9)
	v_mfma_f32_32x32x16_bf16 v[20:35], v[184:187], v[76:79], v[20:35]
	s_waitcnt lgkmcnt(8)
	v_mfma_f32_32x32x16_bf16 v[20:35], v[188:191], v[80:83], v[20:35]
	s_waitcnt lgkmcnt(7)
	v_mfma_f32_32x32x16_bf16 v[20:35], v[192:195], v[84:87], v[20:35]
	s_waitcnt lgkmcnt(6)
	v_mfma_f32_32x32x16_bf16 v[20:35], v[196:199], v[88:91], v[20:35]
	s_waitcnt lgkmcnt(5)
	v_mfma_f32_32x32x16_bf16 v[20:35], v[200:203], v[92:95], v[20:35]
	s_waitcnt lgkmcnt(4)
	v_mfma_f32_32x32x16_bf16 v[20:35], v[204:207], v[96:99], v[20:35]
	ds_read_b64_tr_b16 v[236:237], v211
	ds_read_b64_tr_b16 v[238:239], v211 offset:4352
	ds_read_b64_tr_b16 v[240:241], v211 offset:8704
	ds_read_b64_tr_b16 v[242:243], v211 offset:13056
	s_waitcnt lgkmcnt(4)
	v_sub_f32_e32 v220, v146, v220
	v_sub_f32_e32 v221, v146, v221
	v_sub_f32_e32 v222, v146, v222
	v_sub_f32_e32 v223, v146, v223
	v_sub_f32_e32 v224, v146, v224
	v_sub_f32_e32 v225, v146, v225
	v_sub_f32_e32 v226, v146, v226
	v_sub_f32_e32 v227, v146, v227
	v_sub_f32_e32 v228, v146, v228
	v_sub_f32_e32 v229, v146, v229
	v_sub_f32_e32 v230, v146, v230
	v_sub_f32_e32 v231, v146, v231
	v_sub_f32_e32 v232, v146, v232
	v_sub_f32_e32 v233, v146, v233
	v_sub_f32_e32 v234, v146, v234
	v_sub_f32_e32 v235, v146, v235
	v_exp_f32_e32 v220, v220
	v_exp_f32_e32 v221, v221
	v_exp_f32_e32 v222, v222
	v_exp_f32_e32 v223, v223
	v_exp_f32_e32 v224, v224
	v_exp_f32_e32 v225, v225
	v_exp_f32_e32 v226, v226
	v_exp_f32_e32 v227, v227
	v_exp_f32_e32 v228, v228
	v_exp_f32_e32 v229, v229
	v_exp_f32_e32 v230, v230
	v_exp_f32_e32 v231, v231
	v_exp_f32_e32 v232, v232
	v_exp_f32_e32 v233, v233
	v_exp_f32_e32 v234, v234
	v_exp_f32_e32 v235, v235
	s_cmp_lg_u32 s15, 32
	s_cbranch_scc1 .Ls2_nomask_1
	v_sub_u32_e32 v208, v147, v210
	v_cmp_le_i32_e32 vcc, 0, v208
	v_cmp_le_i32_e64 s[6:7], 1, v208
	s_nop 1
	v_cndmask_b32_e32 v220, 0, v220, vcc
	v_cndmask_b32_e64 v221, 0, v221, s[6:7]
	v_cmp_le_i32_e32 vcc, 2, v208
	v_cmp_le_i32_e64 s[6:7], 3, v208
	s_nop 1
	v_cndmask_b32_e32 v222, 0, v222, vcc
	v_cndmask_b32_e64 v223, 0, v223, s[6:7]
	v_cmp_le_i32_e32 vcc, 8, v208
	v_cmp_le_i32_e64 s[6:7], 9, v208
	s_nop 1
	v_cndmask_b32_e32 v224, 0, v224, vcc
	v_cndmask_b32_e64 v225, 0, v225, s[6:7]
	v_cmp_le_i32_e32 vcc, 10, v208
	v_cmp_le_i32_e64 s[6:7], 11, v208
	s_nop 1
	v_cndmask_b32_e32 v226, 0, v226, vcc
	v_cndmask_b32_e64 v227, 0, v227, s[6:7]
	v_cmp_le_i32_e32 vcc, 16, v208
	v_cmp_le_i32_e64 s[6:7], 17, v208
	s_nop 1
	v_cndmask_b32_e32 v228, 0, v228, vcc
	v_cndmask_b32_e64 v229, 0, v229, s[6:7]
	v_cmp_le_i32_e32 vcc, 18, v208
	v_cmp_le_i32_e64 s[6:7], 19, v208
	s_nop 1
	v_cndmask_b32_e32 v230, 0, v230, vcc
	v_cndmask_b32_e64 v231, 0, v231, s[6:7]
	v_cmp_le_i32_e32 vcc, 24, v208
	v_cmp_le_i32_e64 s[6:7], 25, v208
	s_nop 1
	v_cndmask_b32_e32 v232, 0, v232, vcc
	v_cndmask_b32_e64 v233, 0, v233, s[6:7]
	v_cmp_le_i32_e32 vcc, 26, v208
	v_cmp_le_i32_e64 s[6:7], 27, v208
	s_nop 1
	v_cndmask_b32_e32 v234, 0, v234, vcc
	v_cndmask_b32_e64 v235, 0, v235, s[6:7]
.Ls2_nomask_1:
	v_mul_f32_e32 v20, v20, v220
	v_mul_f32_e32 v21, v21, v221
	v_mul_f32_e32 v22, v22, v222
	v_mul_f32_e32 v23, v23, v223
	v_mul_f32_e32 v24, v24, v224
	v_mul_f32_e32 v25, v25, v225
	v_mul_f32_e32 v26, v26, v226
	v_mul_f32_e32 v27, v27, v227
	v_mul_f32_e32 v28, v28, v228
	v_mul_f32_e32 v29, v29, v229
	v_mul_f32_e32 v30, v30, v230
	v_mul_f32_e32 v31, v31, v231
	v_mul_f32_e32 v32, v32, v232
	v_mul_f32_e32 v33, v33, v233
	v_mul_f32_e32 v34, v34, v234
	v_mul_f32_e32 v35, v35, v235
	v_cvt_pk_bf16_f32 v244, v20, v21
	v_cvt_pk_bf16_f32 v245, v22, v23
	v_cvt_pk_bf16_f32 v246, v24, v25
	v_cvt_pk_bf16_f32 v247, v26, v27
	v_cvt_pk_bf16_f32 v248, v28, v29
	v_cvt_pk_bf16_f32 v249, v30, v31
	v_cvt_pk_bf16_f32 v250, v32, v33
	v_cvt_pk_bf16_f32 v251, v34, v35
	s_waitcnt lgkmcnt(0)
	s_nop 1
	v_mfma_f32_32x32x16_bf16 v[4:19], v[236:239], v[244:247], v[4:19]
	v_mfma_f32_32x32x16_bf16 v[4:19], v[240:243], v[248:251], v[4:19]
	s_add_i32 s15, s15, 32
	s_cmp_lg_u32 s15, 64
	s_cbranch_scc1 .LBB0_1038

.LBB0_1079:
	v_add_u32_e32 v208, 0x11000, v150
	v_add_u32_e32 v209, 0x23000, v2
	v_add_u32_e32 v210, s3, v160
	ds_read_b128 v[176:179], v208
	ds_read_b128 v[180:183], v208 offset:32
	ds_read_b128 v[184:187], v208 offset:64
	ds_read_b128 v[188:191], v208 offset:96
	ds_read_b128 v[192:195], v208 offset:128
	ds_read_b128 v[196:199], v208 offset:160
	ds_read_b128 v[200:203], v208 offset:192
	ds_read_b128 v[204:207], v208 offset:224
	ds_read_b128 v[220:223], v209
	ds_read_b128 v[224:227], v209 offset:32
	ds_read_b128 v[228:231], v209 offset:64
	ds_read_b128 v[232:235], v209 offset:96
	s_waitcnt lgkmcnt(11)
	v_mfma_f32_32x32x16_bf16 v[20:35], v[176:179], v[68:71], 0
	s_waitcnt lgkmcnt(10)
	v_mfma_f32_32x32x16_bf16 v[20:35], v[180:183], v[72:75], v[20:35]
	s_waitcnt lgkmcnt(9)
	v_mfma_f32_32x32x16_bf16 v[20:35], v[184:187], v[76:79], v[20:35]
	s_waitcnt lgkmcnt(8)
	v_mfma_f32_32x32x16_bf16 v[20:35], v[188:191], v[80:83], v[20:35]
	s_waitcnt lgkmcnt(7)
	v_mfma_f32_32x32x16_bf16 v[20:35], v[192:195], v[84:87], v[20:35]
	s_waitcnt lgkmcnt(6)
	v_mfma_f32_32x32x16_bf16 v[20:35], v[196:199], v[88:91], v[20:35]
	s_waitcnt lgkmcnt(5)
	v_mfma_f32_32x32x16_bf16 v[20:35], v[200:203], v[92:95], v[20:35]
	s_waitcnt lgkmcnt(4)
	v_mfma_f32_32x32x16_bf16 v[20:35], v[204:207], v[96:99], v[20:35]
	ds_read_b64_tr_b16 v[236:237], v151
	ds_read_b64_tr_b16 v[238:239], v151 offset:4352
	ds_read_b64_tr_b16 v[240:241], v151 offset:8704
	ds_read_b64_tr_b16 v[242:243], v151 offset:13056
	s_waitcnt lgkmcnt(4)
	v_sub_f32_e32 v220, v155, v220
	v_sub_f32_e32 v221, v155, v221
	v_sub_f32_e32 v222, v155, v222
	v_sub_f32_e32 v223, v155, v223
	v_sub_f32_e32 v224, v155, v224
	v_sub_f32_e32 v225, v155, v225
	v_sub_f32_e32 v226, v155, v226
	v_sub_f32_e32 v227, v155, v227
	v_sub_f32_e32 v228, v155, v228
	v_sub_f32_e32 v229, v155, v229
	v_sub_f32_e32 v230, v155, v230
	v_sub_f32_e32 v231, v155, v231
	v_sub_f32_e32 v232, v155, v232
	v_sub_f32_e32 v233, v155, v233
	v_sub_f32_e32 v234, v155, v234
	v_sub_f32_e32 v235, v155, v235
	v_exp_f32_e32 v220, v220
	v_exp_f32_e32 v221, v221
	v_exp_f32_e32 v222, v222
	v_exp_f32_e32 v223, v223
	v_exp_f32_e32 v224, v224
	v_exp_f32_e32 v225, v225
	v_exp_f32_e32 v226, v226
	v_exp_f32_e32 v227, v227
	v_exp_f32_e32 v228, v228
	v_exp_f32_e32 v229, v229
	v_exp_f32_e32 v230, v230
	v_exp_f32_e32 v231, v231
	v_exp_f32_e32 v232, v232
	v_exp_f32_e32 v233, v233
	v_exp_f32_e32 v234, v234
	v_exp_f32_e32 v235, v235
	s_cmp_lg_u32 s3, 64
	s_cbranch_scc1 .Ls2_nomask_2
	v_sub_u32_e32 v208, v156, v210
	v_cmp_le_i32_e32 vcc, 0, v208
	v_cmp_le_i32_e64 s[6:7], 1, v208
	s_nop 1
	v_cndmask_b32_e32 v220, 0, v220, vcc
	v_cndmask_b32_e64 v221, 0, v221, s[6:7]
	v_cmp_le_i32_e32 vcc, 2, v208
	v_cmp_le_i32_e64 s[6:7], 3, v208
	s_nop 1
	v_cndmask_b32_e32 v222, 0, v222, vcc
	v_cndmask_b32_e64 v223, 0, v223, s[6:7]
	v_cmp_le_i32_e32 vcc, 8, v208
	v_cmp_le_i32_e64 s[6:7], 9, v208
	s_nop 1
	v_cndmask_b32_e32 v224, 0, v224, vcc
	v_cndmask_b32_e64 v225, 0, v225, s[6:7]
	v_cmp_le_i32_e32 vcc, 10, v208
	v_cmp_le_i32_e64 s[6:7], 11, v208
	s_nop 1
	v_cndmask_b32_e32 v226, 0, v226, vcc
	v_cndmask_b32_e64 v227, 0, v227, s[6:7]
	v_cmp_le_i32_e32 vcc, 16, v208
	v_cmp_le_i32_e64 s[6:7], 17, v208
	s_nop 1
	v_cndmask_b32_e32 v228, 0, v228, vcc
	v_cndmask_b32_e64 v229, 0, v229, s[6:7]
	v_cmp_le_i32_e32 vcc, 18, v208
	v_cmp_le_i32_e64 s[6:7], 19, v208
	s_nop 1
	v_cndmask_b32_e32 v230, 0, v230, vcc
	v_cndmask_b32_e64 v231, 0, v231, s[6:7]
	v_cmp_le_i32_e32 vcc, 24, v208
	v_cmp_le_i32_e64 s[6:7], 25, v208
	s_nop 1
	v_cndmask_b32_e32 v232, 0, v232, vcc
	v_cndmask_b32_e64 v233, 0, v233, s[6:7]
	v_cmp_le_i32_e32 vcc, 26, v208
	v_cmp_le_i32_e64 s[6:7], 27, v208
	s_nop 1
	v_cndmask_b32_e32 v234, 0, v234, vcc
	v_cndmask_b32_e64 v235, 0, v235, s[6:7]
.Ls2_nomask_2:
	v_mul_f32_e32 v20, v20, v220
	v_mul_f32_e32 v21, v21, v221
	v_mul_f32_e32 v22, v22, v222
	v_mul_f32_e32 v23, v23, v223
	v_mul_f32_e32 v24, v24, v224
	v_mul_f32_e32 v25, v25, v225
	v_mul_f32_e32 v26, v26, v226
	v_mul_f32_e32 v27, v27, v227
	v_mul_f32_e32 v28, v28, v228
	v_mul_f32_e32 v29, v29, v229
	v_mul_f32_e32 v30, v30, v230
	v_mul_f32_e32 v31, v31, v231
	v_mul_f32_e32 v32, v32, v232
	v_mul_f32_e32 v33, v33, v233
	v_mul_f32_e32 v34, v34, v234
	v_mul_f32_e32 v35, v35, v235
	v_cvt_pk_bf16_f32 v244, v20, v21
	v_cvt_pk_bf16_f32 v245, v22, v23
	v_cvt_pk_bf16_f32 v246, v24, v25
	v_cvt_pk_bf16_f32 v247, v26, v27
	v_cvt_pk_bf16_f32 v248, v28, v29
	v_cvt_pk_bf16_f32 v249, v30, v31
	v_cvt_pk_bf16_f32 v250, v32, v33
	v_cvt_pk_bf16_f32 v251, v34, v35
	s_waitcnt lgkmcnt(0)
	s_nop 1
	v_mfma_f32_32x32x16_bf16 v[4:19], v[236:239], v[244:247], v[4:19]
	v_mfma_f32_32x32x16_bf16 v[4:19], v[240:243], v[248:251], v[4:19]
	s_add_i32 s3, s3, 32
	v_add_u32_e32 v151, 0x4400, v151
	v_add_u32_e32 v150, 0x2400, v150
	v_add_u32_e32 v2, 0x80, v2
	s_cmp_lg_u32 s3, 96
	s_cbranch_scc1 .LBB0_1079

.LBB0_1118:
	v_add_u32_e32 v208, 0x11000, v166
	v_add_u32_e32 v209, 0x23000, v167
	v_add_u32_e32 v210, s3, v160
	ds_read_b128 v[176:179], v208
	ds_read_b128 v[180:183], v208 offset:32
	ds_read_b128 v[184:187], v208 offset:64
	ds_read_b128 v[188:191], v208 offset:96
	ds_read_b128 v[192:195], v208 offset:128
	ds_read_b128 v[196:199], v208 offset:160
	ds_read_b128 v[200:203], v208 offset:192
	ds_read_b128 v[204:207], v208 offset:224
	ds_read_b128 v[220:223], v209
	ds_read_b128 v[224:227], v209 offset:32
	ds_read_b128 v[228:231], v209 offset:64
	ds_read_b128 v[232:235], v209 offset:96
	s_waitcnt lgkmcnt(11)
	v_mfma_f32_32x32x16_bf16 v[20:35], v[176:179], v[68:71], 0
	s_waitcnt lgkmcnt(10)
	v_mfma_f32_32x32x16_bf16 v[20:35], v[180:183], v[72:75], v[20:35]
	s_waitcnt lgkmcnt(9)
	v_mfma_f32_32x32x16_bf16 v[20:35], v[184:187], v[76:79], v[20:35]
	s_waitcnt lgkmcnt(8)
	v_mfma_f32_32x32x16_bf16 v[20:35], v[188:191], v[80:83], v[20:35]
	s_waitcnt lgkmcnt(7)
	v_mfma_f32_32x32x16_bf16 v[20:35], v[192:195], v[84:87], v[20:35]
	s_waitcnt lgkmcnt(6)
	v_mfma_f32_32x32x16_bf16 v[20:35], v[196:199], v[88:91], v[20:35]
	s_waitcnt lgkmcnt(5)
	v_mfma_f32_32x32x16_bf16 v[20:35], v[200:203], v[92:95], v[20:35]
	s_waitcnt lgkmcnt(4)
	v_mfma_f32_32x32x16_bf16 v[20:35], v[204:207], v[96:99], v[20:35]
	ds_read_b64_tr_b16 v[236:237], v165
	ds_read_b64_tr_b16 v[238:239], v165 offset:4352
	ds_read_b64_tr_b16 v[240:241], v165 offset:8704
	ds_read_b64_tr_b16 v[242:243], v165 offset:13056
	s_waitcnt lgkmcnt(4)
	v_sub_f32_e32 v220, v2, v220
	v_sub_f32_e32 v221, v2, v221
	v_sub_f32_e32 v222, v2, v222
	v_sub_f32_e32 v223, v2, v223
	v_sub_f32_e32 v224, v2, v224
	v_sub_f32_e32 v225, v2, v225
	v_sub_f32_e32 v226, v2, v226
	v_sub_f32_e32 v227, v2, v227
	v_sub_f32_e32 v228, v2, v228
	v_sub_f32_e32 v229, v2, v229
	v_sub_f32_e32 v230, v2, v230
	v_sub_f32_e32 v231, v2, v231
	v_sub_f32_e32 v232, v2, v232
	v_sub_f32_e32 v233, v2, v233
	v_sub_f32_e32 v234, v2, v234
	v_sub_f32_e32 v235, v2, v235
	v_exp_f32_e32 v220, v220
	v_exp_f32_e32 v221, v221
	v_exp_f32_e32 v222, v222
	v_exp_f32_e32 v223, v223
	v_exp_f32_e32 v224, v224
	v_exp_f32_e32 v225, v225
	v_exp_f32_e32 v226, v226
	v_exp_f32_e32 v227, v227
	v_exp_f32_e32 v228, v228
	v_exp_f32_e32 v229, v229
	v_exp_f32_e32 v230, v230
	v_exp_f32_e32 v231, v231
	v_exp_f32_e32 v232, v232
	v_exp_f32_e32 v233, v233
	v_exp_f32_e32 v234, v234
	v_exp_f32_e32 v235, v235
	s_cmp_lg_u32 s3, 96
	s_cbranch_scc1 .Ls2_nomask_3
	v_sub_u32_e32 v208, v36, v210
	v_cmp_le_i32_e32 vcc, 0, v208
	v_cmp_le_i32_e64 s[6:7], 1, v208
	s_nop 1
	v_cndmask_b32_e32 v220, 0, v220, vcc
	v_cndmask_b32_e64 v221, 0, v221, s[6:7]
	v_cmp_le_i32_e32 vcc, 2, v208
	v_cmp_le_i32_e64 s[6:7], 3, v208
	s_nop 1
	v_cndmask_b32_e32 v222, 0, v222, vcc
	v_cndmask_b32_e64 v223, 0, v223, s[6:7]
	v_cmp_le_i32_e32 vcc, 8, v208
	v_cmp_le_i32_e64 s[6:7], 9, v208
	s_nop 1
	v_cndmask_b32_e32 v224, 0, v224, vcc
	v_cndmask_b32_e64 v225, 0, v225, s[6:7]
	v_cmp_le_i32_e32 vcc, 10, v208
	v_cmp_le_i32_e64 s[6:7], 11, v208
	s_nop 1
	v_cndmask_b32_e32 v226, 0, v226, vcc
	v_cndmask_b32_e64 v227, 0, v227, s[6:7]
	v_cmp_le_i32_e32 vcc, 16, v208
	v_cmp_le_i32_e64 s[6:7], 17, v208
	s_nop 1
	v_cndmask_b32_e32 v228, 0, v228, vcc
	v_cndmask_b32_e64 v229, 0, v229, s[6:7]
	v_cmp_le_i32_e32 vcc, 18, v208
	v_cmp_le_i32_e64 s[6:7], 19, v208
	s_nop 1
	v_cndmask_b32_e32 v230, 0, v230, vcc
	v_cndmask_b32_e64 v231, 0, v231, s[6:7]
	v_cmp_le_i32_e32 vcc, 24, v208
	v_cmp_le_i32_e64 s[6:7], 25, v208
	s_nop 1
	v_cndmask_b32_e32 v232, 0, v232, vcc
	v_cndmask_b32_e64 v233, 0, v233, s[6:7]
	v_cmp_le_i32_e32 vcc, 26, v208
	v_cmp_le_i32_e64 s[6:7], 27, v208
	s_nop 1
	v_cndmask_b32_e32 v234, 0, v234, vcc
	v_cndmask_b32_e64 v235, 0, v235, s[6:7]
.Ls2_nomask_3:
	v_mul_f32_e32 v20, v20, v220
	v_mul_f32_e32 v21, v21, v221
	v_mul_f32_e32 v22, v22, v222
	v_mul_f32_e32 v23, v23, v223
	v_mul_f32_e32 v24, v24, v224
	v_mul_f32_e32 v25, v25, v225
	v_mul_f32_e32 v26, v26, v226
	v_mul_f32_e32 v27, v27, v227
	v_mul_f32_e32 v28, v28, v228
	v_mul_f32_e32 v29, v29, v229
	v_mul_f32_e32 v30, v30, v230
	v_mul_f32_e32 v31, v31, v231
	v_mul_f32_e32 v32, v32, v232
	v_mul_f32_e32 v33, v33, v233
	v_mul_f32_e32 v34, v34, v234
	v_mul_f32_e32 v35, v35, v235
	v_cvt_pk_bf16_f32 v244, v20, v21
	v_cvt_pk_bf16_f32 v245, v22, v23
	v_cvt_pk_bf16_f32 v246, v24, v25
	v_cvt_pk_bf16_f32 v247, v26, v27
	v_cvt_pk_bf16_f32 v248, v28, v29
	v_cvt_pk_bf16_f32 v249, v30, v31
	v_cvt_pk_bf16_f32 v250, v32, v33
	v_cvt_pk_bf16_f32 v251, v34, v35
	s_waitcnt lgkmcnt(0)
	s_nop 1
	v_mfma_f32_32x32x16_bf16 v[4:19], v[236:239], v[244:247], v[4:19]
	v_mfma_f32_32x32x16_bf16 v[4:19], v[240:243], v[248:251], v[4:19]
	s_add_i32 s3, s3, 32
	v_add_u32_e32 v165, 0x4400, v165
	v_add_u32_e32 v166, 0x2400, v166
	v_add_u32_e32 v167, 0x80, v167
	s_cmp_lg_u32 s3, 128
	s_cbranch_scc1 .LBB0_1118
